# proj post-loop reordered (next-tile prefetch at loop exit, pipelined last k-tile, staged tile written to LDS before the epilogue) + RMSNorm row loops with one-row-ahead prefetch
# speedup vs baseline: 1.0742x; 1.0002x over previous
.LBB0_28:
	s_nop 0
	v_and_b32_e32 v3, 64, v0
	v_add_u32_e32 v3, 64, v3
	v_xor_b32_e32 v4, 32, v0
	v_cmp_lt_i32_e32 vcc, v4, v3
	v_and_b32_e32 v16, 63, v17
	v_ashrrev_i32_e32 v1, 6, v17
	v_cndmask_b32_e32 v4, v0, v4, vcc
	v_lshlrev_b32_e32 v215, 2, v4
	v_xor_b32_e32 v4, 16, v0
	v_cmp_lt_i32_e32 vcc, v4, v3
	s_lshl_b32 s6, s92, 3
	v_lshlrev_b32_e32 v2, 2, v16
	v_cndmask_b32_e32 v4, v0, v4, vcc
	v_lshlrev_b32_e32 v216, 2, v4
	v_xor_b32_e32 v4, 8, v0
	v_cmp_lt_i32_e32 vcc, v4, v3
	s_cmpk_gt_i32 s2, 0x7ff
	v_mov_b32_e32 v19, 0
	v_cndmask_b32_e32 v4, v0, v4, vcc
	v_lshlrev_b32_e32 v217, 2, v4
	v_xor_b32_e32 v4, 4, v0
	v_cmp_lt_i32_e32 vcc, v4, v3
	v_lshl_add_u32 v28, s2, 3, v1
	v_lshlrev_b32_e32 v18, 2, v2
	v_cndmask_b32_e32 v4, v0, v4, vcc
	v_lshlrev_b32_e32 v218, 2, v4
	v_xor_b32_e32 v4, 2, v0
	v_cmp_lt_i32_e32 vcc, v4, v3
	v_lshlrev_b32_e32 v20, 1, v2
	s_nop 0
	v_cndmask_b32_e32 v4, v0, v4, vcc
	v_lshlrev_b32_e32 v219, 2, v4
	v_xor_b32_e32 v4, 1, v0
	v_cmp_lt_i32_e32 vcc, v4, v3
	s_nop 1
	v_cndmask_b32_e32 v0, v0, v4, vcc
	v_lshlrev_b32_e32 v220, 2, v0
	s_cbranch_scc1 .LBB0_31
	s_load_dwordx16 s[8:23], s[0:1], 0x0
	v_mov_b32_e32 v21, v19
	v_lshl_add_u64 v[24:25], s[86:87], 0, v[20:21]
	s_mov_b64 s[4:5], 0xa000000
	v_lshl_add_u64 v[24:25], v[24:25], 0, s[4:5]
	s_waitcnt lgkmcnt(0)
	global_load_dwordx4 v[0:3], v18, s[12:13]
	global_load_dwordx4 v[4:7], v18, s[12:13] offset:1024
	global_load_dwordx4 v[8:11], v18, s[12:13] offset:2048
	global_load_dwordx4 v[12:15], v18, s[12:13] offset:3072
	v_lshl_add_u64 v[22:23], s[8:9], 0, v[18:19]
	v_mov_b32_e32 v19, 0x358637bd
	s_mov_b32 s3, 0x800000
	v_mov_b32_e32 v26, v28
	s_mov_b32 s4, s2
	v_ashrrev_i32_e32 v27, 31, v26
	v_lshlrev_b64 v[30:31], 12, v[26:27]
	v_lshl_add_u64 v[46:47], v[22:23], 0, v[30:31]
	global_load_dwordx4 v[62:65], v[46:47], off
	global_load_dwordx4 v[66:69], v[46:47], off offset:1024
	global_load_dwordx4 v[70:73], v[46:47], off offset:2048
	global_load_dwordx4 v[74:77], v[46:47], off offset:3072
	s_waitcnt vmcnt(0)
	s_branch .Llbb0_30_body
.LBB0_30:
	s_waitcnt vmcnt(4)
.Llbb0_30_body:
	v_ashrrev_i32_e32 v27, 31, v26
	v_lshlrev_b64 v[30:31], 12, v[26:27]
	v_lshl_add_u64 v[46:47], v[22:23], 0, v[30:31]
	v_mov_b32_e32 v30, v62
	v_mov_b32_e32 v31, v63
	v_mov_b32_e32 v32, v64
	v_mov_b32_e32 v33, v65
	v_mov_b32_e32 v34, v66
	v_mov_b32_e32 v35, v67
	v_mov_b32_e32 v36, v68
	v_mov_b32_e32 v37, v69
	v_mov_b32_e32 v38, v70
	v_mov_b32_e32 v39, v71
	v_mov_b32_e32 v40, v72
	v_mov_b32_e32 v41, v73
	v_mov_b32_e32 v42, v74
	v_mov_b32_e32 v43, v75
	v_mov_b32_e32 v44, v76
	v_mov_b32_e32 v45, v77
	s_add_i32 s4, s4, s92
	s_cmpk_gt_i32 s4, 0x7ff
	s_cbranch_scc1 .Llbb0_30_nonext
	v_add_u32_e32 v78, s6, v26
	v_ashrrev_i32_e32 v79, 31, v78
	v_lshlrev_b64 v[80:81], 12, v[78:79]
	v_lshl_add_u64 v[80:81], v[22:23], 0, v[80:81]
	global_load_dwordx4 v[62:65], v[80:81], off
	global_load_dwordx4 v[66:69], v[80:81], off offset:1024
	global_load_dwordx4 v[70:73], v[80:81], off offset:2048
	global_load_dwordx4 v[74:77], v[80:81], off offset:3072
.Llbb0_30_nonext:
	v_mov_b32_e32 v48, v31
	v_mov_b32_e32 v49, v35
	v_mov_b32_e32 v46, v30
	v_mov_b32_e32 v47, v34
	v_mov_b32_e32 v56, v39
	v_mov_b32_e32 v57, v43
	v_pk_mul_f32 v[48:49], v[48:49], v[48:49]
	v_mov_b32_e32 v50, v32
	v_mov_b32_e32 v51, v36
	v_mov_b32_e32 v54, v38
	v_mov_b32_e32 v55, v42
	v_pk_mul_f32 v[56:57], v[56:57], v[56:57]
	v_pk_fma_f32 v[46:47], v[46:47], v[46:47], v[48:49]
	v_mov_b32_e32 v52, v33
	v_mov_b32_e32 v53, v37
	v_mov_b32_e32 v58, v40
	v_mov_b32_e32 v59, v44
	v_pk_fma_f32 v[48:49], v[54:55], v[54:55], v[56:57]
	v_pk_fma_f32 v[46:47], v[50:51], v[50:51], v[46:47]
	v_mov_b32_e32 v60, v41
	v_mov_b32_e32 v61, v45
	v_pk_fma_f32 v[48:49], v[58:59], v[58:59], v[48:49]
	v_pk_fma_f32 v[46:47], v[52:53], v[52:53], v[46:47]
	v_pk_fma_f32 v[48:49], v[60:61], v[60:61], v[48:49]
	v_add_f32_e32 v21, v46, v47
	v_add_f32_e32 v21, v21, v48
	v_add_f32_e32 v21, v21, v49
	ds_bpermute_b32 v29, v215, v21
	v_lshlrev_b64 v[46:47], 11, v[26:27]
	v_lshl_add_u64 v[46:47], v[24:25], 0, v[46:47]
	v_add_u32_e32 v26, s6, v26
	s_waitcnt lgkmcnt(0)
	v_add_f32_e32 v21, v21, v29
	ds_bpermute_b32 v29, v216, v21
	s_waitcnt lgkmcnt(0)
	v_add_f32_e32 v21, v21, v29
	ds_bpermute_b32 v29, v217, v21
	s_waitcnt lgkmcnt(0)
	v_add_f32_e32 v21, v21, v29
	ds_bpermute_b32 v29, v218, v21
	s_waitcnt lgkmcnt(0)
	v_add_f32_e32 v21, v21, v29
	ds_bpermute_b32 v29, v219, v21
	s_waitcnt lgkmcnt(0)
	v_add_f32_e32 v21, v21, v29
	ds_bpermute_b32 v29, v220, v21
	s_waitcnt lgkmcnt(0)
	v_add_f32_e32 v21, v21, v29
	v_fmamk_f32 v21, v21, 0x3a800000, v19
	v_mul_f32_e32 v29, 0x4b800000, v21
	v_cmp_gt_f32_e32 vcc, s3, v21
	s_nop 1
	v_cndmask_b32_e32 v21, v21, v29, vcc
	v_rsq_f32_e32 v21, v21
	s_nop 0
	v_mul_f32_e32 v27, 0x45800000, v21
	v_cndmask_b32_e32 v48, v21, v27, vcc
	v_pk_mul_f32 v[30:31], v[30:31], v[48:49] op_sel_hi:[1,0]
	v_pk_mul_f32 v[32:33], v[32:33], v[48:49] op_sel_hi:[1,0]
	v_pk_mul_f32 v[34:35], v[34:35], v[48:49] op_sel_hi:[1,0]
	v_pk_mul_f32 v[36:37], v[36:37], v[48:49] op_sel_hi:[1,0]
	v_pk_mul_f32 v[38:39], v[38:39], v[48:49] op_sel_hi:[1,0]
	v_pk_mul_f32 v[40:41], v[40:41], v[48:49] op_sel_hi:[1,0]
	v_pk_mul_f32 v[42:43], v[42:43], v[48:49] op_sel_hi:[1,0]
	v_pk_mul_f32 v[44:45], v[44:45], v[48:49] op_sel_hi:[1,0]
	v_pk_mul_f32 v[30:31], v[0:1], v[30:31]
	v_pk_mul_f32 v[32:33], v[2:3], v[32:33]
	v_pk_mul_f32 v[34:35], v[4:5], v[34:35]
	v_pk_mul_f32 v[36:37], v[6:7], v[36:37]
	v_pk_mul_f32 v[38:39], v[8:9], v[38:39]
	v_pk_mul_f32 v[40:41], v[10:11], v[40:41]
	v_pk_mul_f32 v[42:43], v[12:13], v[42:43]
	v_pk_mul_f32 v[44:45], v[14:15], v[44:45]
	v_cvt_pk_bf16_f32 v30, v30, v31
	v_cvt_pk_bf16_f32 v31, v32, v33
	v_cvt_pk_bf16_f32 v32, v34, v35
	v_cvt_pk_bf16_f32 v33, v36, v37
	v_cvt_pk_bf16_f32 v34, v38, v39
	v_cvt_pk_bf16_f32 v35, v40, v41
	v_cvt_pk_bf16_f32 v36, v42, v43
	v_cvt_pk_bf16_f32 v37, v44, v45
	global_store_dwordx2 v[46:47], v[30:31], off
	global_store_dwordx2 v[46:47], v[32:33], off offset:512
	global_store_dwordx2 v[46:47], v[34:35], off offset:1024
	global_store_dwordx2 v[46:47], v[36:37], off offset:1536
	s_cbranch_scc0 .LBB0_30

.Lgk_p0_s15:
	v_lshl_add_u64 v[176:177], v[176:177], 0, s[98:99]
	v_lshl_add_u64 v[184:185], v[184:185], 0, s[98:99]
	v_lshl_add_u64 v[178:179], v[178:179], 0, s[98:99]
	v_lshl_add_u64 v[186:187], v[186:187], 0, s[98:99]
	v_lshl_add_u64 v[180:181], v[180:181], 0, s[98:99]
	v_lshl_add_u64 v[188:189], v[188:189], 0, s[98:99]
	v_lshl_add_u64 v[182:183], v[182:183], 0, s[98:99]
	v_lshl_add_u64 v[190:191], v[190:191], 0, s[98:99]
	s_add_u32 s16, s16, 0x80
	s_waitcnt lgkmcnt(0)
	s_barrier
	s_cmpk_eq_i32 s16, 0x780
	s_cbranch_scc0 .Lgk_p0
	s_add_i32 s19, s66, s92
	s_cmpk_lt_i32 s19, 0x500
	s_cselect_b64 s[16:17], -1, 0
	s_and_b64 vcc, exec, s[16:17]
	s_cbranch_vccz .Lpl_p0_nopf
	s_lshl_b32 s8, s19, 2
	s_and_b32 s20, s8, 0xffffff00
	s_lshl_b32 s8, s19, 19
	s_and_b32 s8, s8, 0x1f80000
	s_add_u32 s70, s22, s8
	s_addc_u32 s71, s23, 0
	s_ashr_i32 s21, s20, 31
	s_lshl_b64 s[20:21], s[20:21], 11
	s_add_u32 s20, s2, s20
	s_addc_u32 s21, s3, s21
	v_lshl_add_u64 v[152:153], s[70:71], 0, v[174:175]
	v_lshl_add_u64 v[154:155], s[20:21], 0, v[174:175]
	v_lshlrev_b64 v[128:129], 1, v[172:173]
	v_lshlrev_b64 v[136:137], 1, v[170:171]
	v_lshlrev_b64 v[144:145], 1, v[168:169]
	v_lshlrev_b64 v[156:157], 1, v[166:167]
	v_lshl_add_u64 v[130:131], v[152:153], 0, v[128:129]
	v_lshl_add_u64 v[132:133], v[154:155], 0, v[128:129]
	v_lshl_add_u64 v[138:139], v[152:153], 0, v[136:137]
	v_lshl_add_u64 v[140:141], v[154:155], 0, v[136:137]
	v_lshl_add_u64 v[146:147], v[152:153], 0, v[144:145]
	v_lshl_add_u64 v[148:149], v[154:155], 0, v[144:145]
	v_lshl_add_u64 v[152:153], v[152:153], 0, v[156:157]
	v_lshl_add_u64 v[156:157], v[154:155], 0, v[156:157]
	global_load_dwordx4 v[128:131], v[130:131], off
	global_load_dwordx4 v[132:135], v[132:133], off
	global_load_dwordx4 v[136:139], v[138:139], off
	global_load_dwordx4 v[140:143], v[140:141], off
	global_load_dwordx4 v[144:147], v[146:147], off
	global_load_dwordx4 v[148:151], v[148:149], off
	global_load_dwordx4 v[152:155], v[152:153], off
	global_load_dwordx4 v[156:159], v[156:157], off
.Lpl_p0_nopf:
	s_mov_b32 s8, 0x10000
	v_add3_u32 v209, v208, v164, 16
	v_add3_u32 v221, v207, v164, 16
	v_add3_u32 v227, v206, v221, s8
	v_add3_u32 v226, v206, v209, s8
	ds_read_b128 v[248:251], v227 offset:32768
	ds_read_b128 v[160:163], v227 offset:36864
	ds_read_b128 v[228:231], v226
	ds_read_b128 v[232:235], v226 offset:4096
	ds_read_b128 v[236:239], v226 offset:8192
	ds_read_b128 v[240:243], v226 offset:12288
	v_add3_u32 v226, v205, v209, s8
	ds_read_b128 v[244:247], v226
	v_add3_u32 v227, v205, v221, s8
	ds_read_b128 v[210:213], v227 offset:32768
	ds_read_b128 v[222:225], v227 offset:36864
	s_waitcnt lgkmcnt(6)
	v_mfma_f32_32x32x16_bf16 v[112:127], v[228:231], v[248:251], v[112:127]
	v_mfma_f32_32x32x16_bf16 v[96:111], v[228:231], v[160:163], v[96:111]
	ds_read_b128 v[228:231], v226 offset:4096
	s_waitcnt lgkmcnt(6)
	v_mfma_f32_32x32x16_bf16 v[80:95], v[232:235], v[248:251], v[80:95]
	v_mfma_f32_32x32x16_bf16 v[64:79], v[232:235], v[160:163], v[64:79]
	ds_read_b128 v[232:235], v226 offset:8192
	s_waitcnt lgkmcnt(6)
	v_mfma_f32_32x32x16_bf16 v[48:63], v[236:239], v[248:251], v[48:63]
	v_mfma_f32_32x32x16_bf16 v[32:47], v[236:239], v[160:163], v[32:47]
	ds_read_b128 v[236:239], v226 offset:12288
	s_waitcnt lgkmcnt(6)
	v_mfma_f32_32x32x16_bf16 v[16:31], v[240:243], v[248:251], v[16:31]
	v_mfma_f32_32x32x16_bf16 v[0:15], v[240:243], v[160:163], v[0:15]
	v_add3_u32 v226, v204, v209, s8
	ds_read_b128 v[240:243], v226
	v_add3_u32 v227, v204, v221, s8
	ds_read_b128 v[248:251], v227 offset:32768
	ds_read_b128 v[160:163], v227 offset:36864
	s_waitcnt lgkmcnt(6)
	v_mfma_f32_32x32x16_bf16 v[112:127], v[244:247], v[210:213], v[112:127]
	v_mfma_f32_32x32x16_bf16 v[96:111], v[244:247], v[222:225], v[96:111]
	ds_read_b128 v[244:247], v226 offset:4096
	s_waitcnt lgkmcnt(6)
	v_mfma_f32_32x32x16_bf16 v[80:95], v[228:231], v[210:213], v[80:95]
	v_mfma_f32_32x32x16_bf16 v[64:79], v[228:231], v[222:225], v[64:79]
	ds_read_b128 v[228:231], v226 offset:8192
	s_waitcnt lgkmcnt(6)
	v_mfma_f32_32x32x16_bf16 v[48:63], v[232:235], v[210:213], v[48:63]
	v_mfma_f32_32x32x16_bf16 v[32:47], v[232:235], v[222:225], v[32:47]
	ds_read_b128 v[232:235], v226 offset:12288
	s_waitcnt lgkmcnt(6)
	v_mfma_f32_32x32x16_bf16 v[16:31], v[236:239], v[210:213], v[16:31]
	v_mfma_f32_32x32x16_bf16 v[0:15], v[236:239], v[222:225], v[0:15]
	v_add3_u32 v226, v203, v209, s8
	ds_read_b128 v[236:239], v226
	v_add3_u32 v227, v203, v221, s8
	ds_read_b128 v[210:213], v227 offset:32768
	ds_read_b128 v[222:225], v227 offset:36864
	s_waitcnt lgkmcnt(6)
	v_mfma_f32_32x32x16_bf16 v[112:127], v[240:243], v[248:251], v[112:127]
	v_mfma_f32_32x32x16_bf16 v[96:111], v[240:243], v[160:163], v[96:111]
	ds_read_b128 v[240:243], v226 offset:4096
	s_waitcnt lgkmcnt(6)
	v_mfma_f32_32x32x16_bf16 v[80:95], v[244:247], v[248:251], v[80:95]
	v_mfma_f32_32x32x16_bf16 v[64:79], v[244:247], v[160:163], v[64:79]
	ds_read_b128 v[244:247], v226 offset:8192
	s_waitcnt lgkmcnt(6)
	v_mfma_f32_32x32x16_bf16 v[48:63], v[228:231], v[248:251], v[48:63]
	v_mfma_f32_32x32x16_bf16 v[32:47], v[228:231], v[160:163], v[32:47]
	ds_read_b128 v[228:231], v226 offset:12288
	s_waitcnt lgkmcnt(6)
	v_mfma_f32_32x32x16_bf16 v[16:31], v[232:235], v[248:251], v[16:31]
	v_mfma_f32_32x32x16_bf16 v[0:15], v[232:235], v[160:163], v[0:15]
	s_waitcnt lgkmcnt(3)
	v_mfma_f32_32x32x16_bf16 v[112:127], v[236:239], v[210:213], v[112:127]
	v_mfma_f32_32x32x16_bf16 v[96:111], v[236:239], v[222:225], v[96:111]
	s_waitcnt lgkmcnt(2)
	v_mfma_f32_32x32x16_bf16 v[80:95], v[240:243], v[210:213], v[80:95]
	v_mfma_f32_32x32x16_bf16 v[64:79], v[240:243], v[222:225], v[64:79]
	s_waitcnt lgkmcnt(1)
	v_mfma_f32_32x32x16_bf16 v[48:63], v[244:247], v[210:213], v[48:63]
	v_mfma_f32_32x32x16_bf16 v[32:47], v[244:247], v[222:225], v[32:47]
	s_waitcnt lgkmcnt(0)
	v_mfma_f32_32x32x16_bf16 v[16:31], v[228:231], v[210:213], v[16:31]
	v_mfma_f32_32x32x16_bf16 v[0:15], v[228:231], v[222:225], v[0:15]
	s_waitcnt lgkmcnt(0)
	s_barrier
	s_and_b64 vcc, exec, s[16:17]
	s_cbranch_vccz .LBB0_357
	s_waitcnt vmcnt(0)
	v_add_u32_e32 v253, 16, v195
	ds_write_b128 v253, v[128:131]
	ds_write_b128 v253, v[132:135] offset:32768
	ds_write_b128 v253, v[136:139] offset:8192
	ds_write_b128 v253, v[140:143] offset:40960
	ds_write_b128 v253, v[144:147] offset:16384
	ds_write_b128 v253, v[148:151] offset:49152
	ds_write_b128 v253, v[152:155] offset:24576
	ds_write_b128 v253, v[156:159] offset:57344

.LBB0_366:
	s_mov_b64 s[16:17], 0
	s_branch .LBB0_348

.LBB0_674:
	s_or_b64 exec, exec, s[0:1]
	v_mov_b32_e32 v16, v214
	v_readlane_b32 s0, v252, 38
	s_waitcnt lgkmcnt(0)
	s_barrier
	s_cmpk_gt_i32 s0, 0x7ff
	s_cbranch_scc1 .LBB0_677
	v_lshlrev_b32_e32 v0, 2, v16
	v_and_b32_e32 v24, 0xfc, v0
	v_readlane_b32 s36, v252, 6
	v_lshlrev_b32_e32 v18, 2, v24
	v_mov_b32_e32 v19, 0
	v_readlane_b32 s40, v252, 10
	v_readlane_b32 s41, v252, 11
	s_mov_b64 s[2:3], 0x1000
	s_movk_i32 s1, 0x1000
	v_lshl_add_u64 v[0:1], s[40:41], 0, v[18:19]
	v_lshl_add_u64 v[20:21], v[0:1], 0, s[2:3]
	v_add_co_u32_e32 v22, vcc, s1, v0
	s_mov_b64 s[2:3], 0xa000000
	s_nop 0
	v_addc_co_u32_e32 v23, vcc, 0, v1, vcc
	global_load_dwordx4 v[0:3], v[20:21], off offset:1024
	global_load_dwordx4 v[4:7], v[20:21], off offset:2048
	global_load_dwordx4 v[8:11], v[22:23], off
	global_load_dwordx4 v[12:15], v[20:21], off offset:3072
	v_ashrrev_i32_e32 v20, 6, v16
	v_lshl_add_u64 v[16:17], s[84:85], 0, v[18:19]
	v_lshlrev_b32_e32 v18, 1, v24
	v_lshl_add_u64 v[18:19], s[86:87], 0, v[18:19]
	v_lshl_add_u64 v[18:19], v[18:19], 0, s[2:3]
	v_lshl_add_u32 v20, s0, 3, v20
	v_mov_b32_e32 v22, 0x358637bd
	s_mov_b32 s1, 0x800000
	v_readlane_b32 s37, v252, 7
	v_readlane_b32 s38, v252, 8
	v_readlane_b32 s39, v252, 9
	v_readlane_b32 s42, v252, 12
	v_readlane_b32 s43, v252, 13
	v_readlane_b32 s44, v252, 14
	v_readlane_b32 s45, v252, 15
	v_readlane_b32 s46, v252, 16
	v_readlane_b32 s47, v252, 17
	v_readlane_b32 s48, v252, 18
	v_readlane_b32 s49, v252, 19
	v_readlane_b32 s50, v252, 20
	v_readlane_b32 s51, v252, 21
	v_ashrrev_i32_e32 v21, 31, v20
	v_lshlrev_b64 v[24:25], 12, v[20:21]
	v_lshl_add_u64 v[40:41], v[16:17], 0, v[24:25]
	global_load_dwordx4 v[62:65], v[40:41], off
	global_load_dwordx4 v[66:69], v[40:41], off offset:1024
	global_load_dwordx4 v[70:73], v[40:41], off offset:2048
	global_load_dwordx4 v[74:77], v[40:41], off offset:3072
	s_waitcnt vmcnt(0)
	s_branch .Llbb0_676_body

.Llbb0_676_body:
	v_ashrrev_i32_e32 v21, 31, v20
	v_lshlrev_b64 v[24:25], 12, v[20:21]
	v_lshl_add_u64 v[40:41], v[16:17], 0, v[24:25]
	v_mov_b32_e32 v24, v62
	v_mov_b32_e32 v25, v63
	v_mov_b32_e32 v26, v64
	v_mov_b32_e32 v27, v65
	v_mov_b32_e32 v28, v66
	v_mov_b32_e32 v29, v67
	v_mov_b32_e32 v30, v68
	v_mov_b32_e32 v31, v69
	v_mov_b32_e32 v32, v70
	v_mov_b32_e32 v33, v71
	v_mov_b32_e32 v34, v72
	v_mov_b32_e32 v35, v73
	v_mov_b32_e32 v36, v74
	v_mov_b32_e32 v37, v75
	v_mov_b32_e32 v38, v76
	v_mov_b32_e32 v39, v77
	s_add_i32 s0, s0, s92
	s_cmpk_lt_i32 s0, 0x800
	s_cbranch_scc0 .Llbb0_676_nonext
	v_add_u32_e32 v78, s16, v20
	v_ashrrev_i32_e32 v79, 31, v78
	v_lshlrev_b64 v[80:81], 12, v[78:79]
	v_lshl_add_u64 v[80:81], v[16:17], 0, v[80:81]
	global_load_dwordx4 v[62:65], v[80:81], off
	global_load_dwordx4 v[66:69], v[80:81], off offset:1024
	global_load_dwordx4 v[70:73], v[80:81], off offset:2048
	global_load_dwordx4 v[74:77], v[80:81], off offset:3072
.Llbb0_676_nonext:
	v_mov_b32_e32 v42, v25
	v_mov_b32_e32 v43, v29
	v_mov_b32_e32 v40, v24
	v_mov_b32_e32 v41, v28
	v_mov_b32_e32 v50, v33
	v_mov_b32_e32 v51, v37
	v_pk_mul_f32 v[42:43], v[42:43], v[42:43]
	v_mov_b32_e32 v44, v26
	v_mov_b32_e32 v45, v30
	v_mov_b32_e32 v48, v32
	v_mov_b32_e32 v49, v36
	v_pk_mul_f32 v[50:51], v[50:51], v[50:51]
	v_pk_fma_f32 v[40:41], v[40:41], v[40:41], v[42:43]
	v_mov_b32_e32 v46, v27
	v_mov_b32_e32 v47, v31
	v_mov_b32_e32 v52, v34
	v_mov_b32_e32 v53, v38
	v_pk_fma_f32 v[42:43], v[48:49], v[48:49], v[50:51]
	v_pk_fma_f32 v[40:41], v[44:45], v[44:45], v[40:41]
	v_mov_b32_e32 v54, v35
	v_mov_b32_e32 v55, v39
	v_pk_fma_f32 v[42:43], v[52:53], v[52:53], v[42:43]
	v_pk_fma_f32 v[40:41], v[46:47], v[46:47], v[40:41]
	v_pk_fma_f32 v[42:43], v[54:55], v[54:55], v[42:43]
	v_add_f32_e32 v23, v40, v41
	v_add_f32_e32 v23, v23, v42
	v_add_f32_e32 v23, v23, v43
	ds_bpermute_b32 v40, v215, v23
	s_waitcnt lgkmcnt(0)
	v_add_f32_e32 v23, v23, v40
	ds_bpermute_b32 v40, v216, v23
	s_waitcnt lgkmcnt(0)
	v_add_f32_e32 v23, v23, v40
	ds_bpermute_b32 v40, v217, v23
	s_waitcnt lgkmcnt(0)
	v_add_f32_e32 v23, v23, v40
	ds_bpermute_b32 v40, v218, v23
	s_waitcnt lgkmcnt(0)
	v_add_f32_e32 v23, v23, v40
	ds_bpermute_b32 v40, v219, v23
	s_waitcnt lgkmcnt(0)
	v_add_f32_e32 v23, v23, v40
	ds_bpermute_b32 v40, v220, v23
	s_waitcnt lgkmcnt(0)
	v_add_f32_e32 v23, v23, v40
	v_fmamk_f32 v23, v23, 0x3a800000, v22
	v_mul_f32_e32 v40, 0x4b800000, v23
	v_cmp_gt_f32_e32 vcc, s1, v23
	s_nop 1
	v_cndmask_b32_e32 v23, v23, v40, vcc
	v_rsq_f32_e32 v23, v23
	v_lshlrev_b64 v[40:41], 11, v[20:21]
	v_lshl_add_u64 v[40:41], v[18:19], 0, v[40:41]
	v_add_u32_e32 v20, s16, v20
	v_mul_f32_e32 v21, 0x45800000, v23
	v_cndmask_b32_e32 v42, v23, v21, vcc
	v_pk_mul_f32 v[24:25], v[24:25], v[42:43] op_sel_hi:[1,0]
	v_pk_mul_f32 v[26:27], v[26:27], v[42:43] op_sel_hi:[1,0]
	v_pk_mul_f32 v[28:29], v[28:29], v[42:43] op_sel_hi:[1,0]
	v_pk_mul_f32 v[30:31], v[30:31], v[42:43] op_sel_hi:[1,0]
	v_pk_mul_f32 v[32:33], v[32:33], v[42:43] op_sel_hi:[1,0]
	v_pk_mul_f32 v[34:35], v[34:35], v[42:43] op_sel_hi:[1,0]
	v_pk_mul_f32 v[36:37], v[36:37], v[42:43] op_sel_hi:[1,0]
	v_pk_mul_f32 v[38:39], v[38:39], v[42:43] op_sel_hi:[1,0]
	v_pk_mul_f32 v[24:25], v[8:9], v[24:25]
	v_pk_mul_f32 v[26:27], v[10:11], v[26:27]
	v_pk_mul_f32 v[28:29], v[0:1], v[28:29]
	v_pk_mul_f32 v[30:31], v[2:3], v[30:31]
	v_pk_mul_f32 v[32:33], v[4:5], v[32:33]
	v_pk_mul_f32 v[34:35], v[6:7], v[34:35]
	v_pk_mul_f32 v[36:37], v[12:13], v[36:37]
	v_pk_mul_f32 v[38:39], v[14:15], v[38:39]
	v_cvt_pk_bf16_f32 v24, v24, v25
	v_cvt_pk_bf16_f32 v25, v26, v27
	v_cvt_pk_bf16_f32 v26, v28, v29
	v_cvt_pk_bf16_f32 v27, v30, v31
	v_cvt_pk_bf16_f32 v28, v32, v33
	v_cvt_pk_bf16_f32 v29, v34, v35
	v_cvt_pk_bf16_f32 v30, v36, v37
	v_cvt_pk_bf16_f32 v31, v38, v39
	global_store_dwordx2 v[40:41], v[24:25], off
	global_store_dwordx2 v[40:41], v[26:27], off offset:512
	global_store_dwordx2 v[40:41], v[28:29], off offset:1024
	global_store_dwordx2 v[40:41], v[30:31], off offset:1536
	s_cbranch_scc1 .LBB0_676

.Lgk_p1_s15:
	v_lshl_add_u64 v[176:177], v[176:177], 0, s[98:99]
	v_lshl_add_u64 v[184:185], v[184:185], 0, s[98:99]
	v_lshl_add_u64 v[178:179], v[178:179], 0, s[98:99]
	v_lshl_add_u64 v[186:187], v[186:187], 0, s[98:99]
	v_lshl_add_u64 v[180:181], v[180:181], 0, s[98:99]
	v_lshl_add_u64 v[188:189], v[188:189], 0, s[98:99]
	v_lshl_add_u64 v[182:183], v[182:183], 0, s[98:99]
	v_lshl_add_u64 v[190:191], v[190:191], 0, s[98:99]
	s_add_u32 s10, s10, 0x80
	s_waitcnt lgkmcnt(0)
	s_barrier
	s_cmpk_eq_i32 s10, 0x780
	s_cbranch_scc0 .Lgk_p1
	s_add_i32 s13, s68, s92
	s_cmpk_lt_i32 s13, 0x500
	s_cselect_b64 s[10:11], -1, 0
	s_and_b64 vcc, exec, s[10:11]
	s_cbranch_vccz .Lpl_p1_nopf
	s_lshl_b32 s8, s13, 2
	s_and_b32 s14, s8, 0xffffff00
	s_lshl_b32 s8, s13, 19
	s_and_b32 s8, s8, 0x1f80000
	s_add_u32 s70, s16, s8
	s_addc_u32 s71, s17, 0
	s_ashr_i32 s15, s14, 31
	s_lshl_b64 s[14:15], s[14:15], 11
	s_add_u32 s14, s2, s14
	s_addc_u32 s15, s3, s15
	v_lshl_add_u64 v[152:153], s[70:71], 0, v[174:175]
	v_lshl_add_u64 v[154:155], s[14:15], 0, v[174:175]
	v_lshlrev_b64 v[128:129], 1, v[166:167]
	v_lshlrev_b64 v[136:137], 1, v[168:169]
	v_lshlrev_b64 v[144:145], 1, v[170:171]
	v_lshlrev_b64 v[156:157], 1, v[172:173]
	v_lshl_add_u64 v[130:131], v[152:153], 0, v[128:129]
	v_lshl_add_u64 v[132:133], v[154:155], 0, v[128:129]
	v_lshl_add_u64 v[138:139], v[152:153], 0, v[136:137]
	v_lshl_add_u64 v[140:141], v[154:155], 0, v[136:137]
	v_lshl_add_u64 v[146:147], v[152:153], 0, v[144:145]
	v_lshl_add_u64 v[148:149], v[154:155], 0, v[144:145]
	v_lshl_add_u64 v[152:153], v[152:153], 0, v[156:157]
	v_lshl_add_u64 v[156:157], v[154:155], 0, v[156:157]
	global_load_dwordx4 v[128:131], v[130:131], off
	global_load_dwordx4 v[132:135], v[132:133], off
	global_load_dwordx4 v[136:139], v[138:139], off
	global_load_dwordx4 v[140:143], v[140:141], off
	global_load_dwordx4 v[144:147], v[146:147], off
	global_load_dwordx4 v[148:151], v[148:149], off
	global_load_dwordx4 v[152:155], v[152:153], off
	global_load_dwordx4 v[156:159], v[156:157], off
.Lpl_p1_nopf:
	s_mov_b32 s8, 0x10000
	v_add3_u32 v164, v205, v203, 16
	v_add3_u32 v221, v204, v203, 16
	v_add3_u32 v227, v209, v221, s8
	v_add3_u32 v226, v209, v164, s8
	ds_read_b128 v[248:251], v227 offset:32768
	ds_read_b128 v[160:163], v227 offset:36864
	ds_read_b128 v[228:231], v226
	ds_read_b128 v[232:235], v226 offset:4096
	ds_read_b128 v[236:239], v226 offset:8192
	ds_read_b128 v[240:243], v226 offset:12288
	v_add3_u32 v226, v208, v164, s8
	ds_read_b128 v[244:247], v226
	v_add3_u32 v227, v208, v221, s8
	ds_read_b128 v[210:213], v227 offset:32768
	ds_read_b128 v[222:225], v227 offset:36864
	s_waitcnt lgkmcnt(6)
	v_mfma_f32_32x32x16_bf16 v[112:127], v[228:231], v[248:251], v[112:127]
	v_mfma_f32_32x32x16_bf16 v[96:111], v[228:231], v[160:163], v[96:111]
	ds_read_b128 v[228:231], v226 offset:4096
	s_waitcnt lgkmcnt(6)
	v_mfma_f32_32x32x16_bf16 v[80:95], v[232:235], v[248:251], v[80:95]
	v_mfma_f32_32x32x16_bf16 v[64:79], v[232:235], v[160:163], v[64:79]
	ds_read_b128 v[232:235], v226 offset:8192
	s_waitcnt lgkmcnt(6)
	v_mfma_f32_32x32x16_bf16 v[48:63], v[236:239], v[248:251], v[48:63]
	v_mfma_f32_32x32x16_bf16 v[32:47], v[236:239], v[160:163], v[32:47]
	ds_read_b128 v[236:239], v226 offset:12288
	s_waitcnt lgkmcnt(6)
	v_mfma_f32_32x32x16_bf16 v[16:31], v[240:243], v[248:251], v[16:31]
	v_mfma_f32_32x32x16_bf16 v[0:15], v[240:243], v[160:163], v[0:15]
	v_add3_u32 v226, v207, v164, s8
	ds_read_b128 v[240:243], v226
	v_add3_u32 v227, v207, v221, s8
	ds_read_b128 v[248:251], v227 offset:32768
	ds_read_b128 v[160:163], v227 offset:36864
	s_waitcnt lgkmcnt(6)
	v_mfma_f32_32x32x16_bf16 v[112:127], v[244:247], v[210:213], v[112:127]
	v_mfma_f32_32x32x16_bf16 v[96:111], v[244:247], v[222:225], v[96:111]
	ds_read_b128 v[244:247], v226 offset:4096
	s_waitcnt lgkmcnt(6)
	v_mfma_f32_32x32x16_bf16 v[80:95], v[228:231], v[210:213], v[80:95]
	v_mfma_f32_32x32x16_bf16 v[64:79], v[228:231], v[222:225], v[64:79]
	ds_read_b128 v[228:231], v226 offset:8192
	s_waitcnt lgkmcnt(6)
	v_mfma_f32_32x32x16_bf16 v[48:63], v[232:235], v[210:213], v[48:63]
	v_mfma_f32_32x32x16_bf16 v[32:47], v[232:235], v[222:225], v[32:47]
	ds_read_b128 v[232:235], v226 offset:12288
	s_waitcnt lgkmcnt(6)
	v_mfma_f32_32x32x16_bf16 v[16:31], v[236:239], v[210:213], v[16:31]
	v_mfma_f32_32x32x16_bf16 v[0:15], v[236:239], v[222:225], v[0:15]
	v_add3_u32 v226, v206, v164, s8
	ds_read_b128 v[236:239], v226
	v_add3_u32 v227, v206, v221, s8
	ds_read_b128 v[210:213], v227 offset:32768
	ds_read_b128 v[222:225], v227 offset:36864
	s_waitcnt lgkmcnt(6)
	v_mfma_f32_32x32x16_bf16 v[112:127], v[240:243], v[248:251], v[112:127]
	v_mfma_f32_32x32x16_bf16 v[96:111], v[240:243], v[160:163], v[96:111]
	ds_read_b128 v[240:243], v226 offset:4096
	s_waitcnt lgkmcnt(6)
	v_mfma_f32_32x32x16_bf16 v[80:95], v[244:247], v[248:251], v[80:95]
	v_mfma_f32_32x32x16_bf16 v[64:79], v[244:247], v[160:163], v[64:79]
	ds_read_b128 v[244:247], v226 offset:8192
	s_waitcnt lgkmcnt(6)
	v_mfma_f32_32x32x16_bf16 v[48:63], v[228:231], v[248:251], v[48:63]
	v_mfma_f32_32x32x16_bf16 v[32:47], v[228:231], v[160:163], v[32:47]
	ds_read_b128 v[228:231], v226 offset:12288
	s_waitcnt lgkmcnt(6)
	v_mfma_f32_32x32x16_bf16 v[16:31], v[232:235], v[248:251], v[16:31]
	v_mfma_f32_32x32x16_bf16 v[0:15], v[232:235], v[160:163], v[0:15]
	s_waitcnt lgkmcnt(3)
	v_mfma_f32_32x32x16_bf16 v[112:127], v[236:239], v[210:213], v[112:127]
	v_mfma_f32_32x32x16_bf16 v[96:111], v[236:239], v[222:225], v[96:111]
	s_waitcnt lgkmcnt(2)
	v_mfma_f32_32x32x16_bf16 v[80:95], v[240:243], v[210:213], v[80:95]
	v_mfma_f32_32x32x16_bf16 v[64:79], v[240:243], v[222:225], v[64:79]
	s_waitcnt lgkmcnt(1)
	v_mfma_f32_32x32x16_bf16 v[48:63], v[244:247], v[210:213], v[48:63]
	v_mfma_f32_32x32x16_bf16 v[32:47], v[244:247], v[222:225], v[32:47]
	s_waitcnt lgkmcnt(0)
	v_mfma_f32_32x32x16_bf16 v[16:31], v[228:231], v[210:213], v[16:31]
	v_mfma_f32_32x32x16_bf16 v[0:15], v[228:231], v[222:225], v[0:15]
	s_waitcnt lgkmcnt(0)
	s_barrier
	s_and_b64 vcc, exec, s[10:11]
	s_cbranch_vccz .LBB0_740
	s_waitcnt vmcnt(0)
	v_add_u32_e32 v253, 16, v195
	ds_write_b128 v253, v[128:131]
	ds_write_b128 v253, v[132:135] offset:32768
	ds_write_b128 v253, v[136:139] offset:8192
	ds_write_b128 v253, v[140:143] offset:40960
	ds_write_b128 v253, v[144:147] offset:16384
	ds_write_b128 v253, v[148:151] offset:49152
	ds_write_b128 v253, v[152:155] offset:24576
	ds_write_b128 v253, v[156:159] offset:57344

.LBB0_749:
	s_mov_b64 s[10:11], 0
	s_branch .LBB0_731

.LBB0_1047:
	s_or_b64 exec, exec, s[0:1]
	s_waitcnt lgkmcnt(0)
	s_barrier
	s_cmpk_gt_i32 s48, 0x7ff
	s_cbranch_scc1 .LBB0_1050
	v_lshlrev_b32_e32 v0, 4, v214
	v_readlane_b32 s0, v252, 22
	v_and_b32_e32 v16, 0x3f0, v0
	v_readlane_b32 s14, v252, 36
	v_readlane_b32 s15, v252, 37
	s_nop 4
	global_load_dwordx4 v[0:3], v16, s[14:15]
	global_load_dwordx4 v[4:7], v16, s[14:15] offset:1024
	global_load_dwordx4 v[8:11], v16, s[14:15] offset:2048
	global_load_dwordx4 v[12:15], v16, s[14:15] offset:3072
	v_ashrrev_i32_e32 v18, 6, v214
	v_mov_b32_e32 v17, 0
	v_lshl_add_u64 v[16:17], s[84:85], 0, v[16:17]
	v_lshl_add_u32 v18, s48, 3, v18
	v_mov_b32_e32 v20, 0x358637bd
	s_mov_b32 s0, 0x800000
	v_readlane_b32 s1, v252, 23
	v_readlane_b32 s2, v252, 24
	v_readlane_b32 s3, v252, 25
	v_readlane_b32 s4, v252, 26
	v_readlane_b32 s5, v252, 27
	v_readlane_b32 s6, v252, 28
	v_readlane_b32 s7, v252, 29
	v_readlane_b32 s8, v252, 30
	v_readlane_b32 s9, v252, 31
	v_readlane_b32 s10, v252, 32
	v_readlane_b32 s11, v252, 33
	v_readlane_b32 s12, v252, 34
	v_readlane_b32 s13, v252, 35
	v_ashrrev_i32_e32 v19, 31, v18
	v_lshlrev_b64 v[22:23], 12, v[18:19]
	v_lshl_add_u64 v[38:39], v[16:17], 0, v[22:23]
	global_load_dwordx4 v[62:65], v[38:39], off
	global_load_dwordx4 v[66:69], v[38:39], off offset:1024
	global_load_dwordx4 v[70:73], v[38:39], off offset:2048
	global_load_dwordx4 v[74:77], v[38:39], off offset:3072
	s_waitcnt vmcnt(0)
	s_branch .Llbb0_1049_body

.Llbb0_1049_body:
	v_ashrrev_i32_e32 v19, 31, v18
	v_lshlrev_b64 v[22:23], 12, v[18:19]
	v_lshl_add_u64 v[38:39], v[16:17], 0, v[22:23]
	v_mov_b32_e32 v22, v62
	v_mov_b32_e32 v23, v63
	v_mov_b32_e32 v24, v64
	v_mov_b32_e32 v25, v65
	v_mov_b32_e32 v26, v66
	v_mov_b32_e32 v27, v67
	v_mov_b32_e32 v28, v68
	v_mov_b32_e32 v29, v69
	v_mov_b32_e32 v30, v70
	v_mov_b32_e32 v31, v71
	v_mov_b32_e32 v32, v72
	v_mov_b32_e32 v33, v73
	v_mov_b32_e32 v34, v74
	v_mov_b32_e32 v35, v75
	v_mov_b32_e32 v36, v76
	v_mov_b32_e32 v37, v77
	s_add_i32 s48, s48, s50
	s_cmpk_lt_i32 s48, 0x800
	s_cbranch_scc0 .Llbb0_1049_nonext
	v_add_u32_e32 v78, s16, v18
	v_ashrrev_i32_e32 v79, 31, v78
	v_lshlrev_b64 v[80:81], 12, v[78:79]
	v_lshl_add_u64 v[80:81], v[16:17], 0, v[80:81]
	global_load_dwordx4 v[62:65], v[80:81], off
	global_load_dwordx4 v[66:69], v[80:81], off offset:1024
	global_load_dwordx4 v[70:73], v[80:81], off offset:2048
	global_load_dwordx4 v[74:77], v[80:81], off offset:3072
.Llbb0_1049_nonext:
	v_add_u32_e32 v18, s16, v18
	v_mov_b32_e32 v42, v23
	v_mov_b32_e32 v43, v27
	v_mov_b32_e32 v40, v22
	v_mov_b32_e32 v41, v26
	v_mov_b32_e32 v50, v31
	v_mov_b32_e32 v51, v35
	v_pk_mul_f32 v[42:43], v[42:43], v[42:43]
	v_mov_b32_e32 v44, v24
	v_mov_b32_e32 v45, v28
	v_mov_b32_e32 v48, v30
	v_mov_b32_e32 v49, v34
	v_pk_mul_f32 v[50:51], v[50:51], v[50:51]
	v_pk_fma_f32 v[40:41], v[40:41], v[40:41], v[42:43]
	v_mov_b32_e32 v46, v25
	v_mov_b32_e32 v47, v29
	v_mov_b32_e32 v52, v32
	v_mov_b32_e32 v53, v36
	v_pk_fma_f32 v[42:43], v[48:49], v[48:49], v[50:51]
	v_pk_fma_f32 v[40:41], v[44:45], v[44:45], v[40:41]
	v_mov_b32_e32 v54, v33
	v_mov_b32_e32 v55, v37
	v_pk_fma_f32 v[42:43], v[52:53], v[52:53], v[42:43]
	v_pk_fma_f32 v[40:41], v[46:47], v[46:47], v[40:41]
	v_pk_fma_f32 v[42:43], v[54:55], v[54:55], v[42:43]
	v_add_f32_e32 v19, v40, v41
	v_add_f32_e32 v19, v19, v42
	v_add_f32_e32 v19, v19, v43
	ds_bpermute_b32 v21, v215, v19
	s_waitcnt lgkmcnt(0)
	v_add_f32_e32 v19, v19, v21
	ds_bpermute_b32 v21, v216, v19
	s_waitcnt lgkmcnt(0)
	v_add_f32_e32 v19, v19, v21
	ds_bpermute_b32 v21, v217, v19
	s_waitcnt lgkmcnt(0)
	v_add_f32_e32 v19, v19, v21
	ds_bpermute_b32 v21, v218, v19
	s_waitcnt lgkmcnt(0)
	v_add_f32_e32 v19, v19, v21
	ds_bpermute_b32 v21, v219, v19
	s_waitcnt lgkmcnt(0)
	v_add_f32_e32 v19, v19, v21
	ds_bpermute_b32 v21, v220, v19
	s_waitcnt lgkmcnt(0)
	v_add_f32_e32 v19, v19, v21
	v_fmamk_f32 v19, v19, 0x3a800000, v20
	v_mul_f32_e32 v21, 0x4b800000, v19
	v_cmp_gt_f32_e32 vcc, s0, v19
	s_nop 1
	v_cndmask_b32_e32 v19, v19, v21, vcc
	v_rsq_f32_e32 v19, v19
	s_nop 0
	v_mul_f32_e32 v21, 0x45800000, v19
	v_cndmask_b32_e32 v40, v19, v21, vcc
	v_pk_mul_f32 v[22:23], v[22:23], v[40:41] op_sel_hi:[1,0]
	v_pk_mul_f32 v[24:25], v[24:25], v[40:41] op_sel_hi:[1,0]
	v_pk_mul_f32 v[26:27], v[26:27], v[40:41] op_sel_hi:[1,0]
	v_pk_mul_f32 v[28:29], v[28:29], v[40:41] op_sel_hi:[1,0]
	v_pk_mul_f32 v[30:31], v[30:31], v[40:41] op_sel_hi:[1,0]
	v_pk_mul_f32 v[32:33], v[32:33], v[40:41] op_sel_hi:[1,0]
	v_pk_mul_f32 v[34:35], v[34:35], v[40:41] op_sel_hi:[1,0]
	v_pk_mul_f32 v[36:37], v[36:37], v[40:41] op_sel_hi:[1,0]
	v_pk_mul_f32 v[24:25], v[2:3], v[24:25]
	v_pk_mul_f32 v[22:23], v[0:1], v[22:23]
	v_pk_mul_f32 v[28:29], v[6:7], v[28:29]
	v_pk_mul_f32 v[26:27], v[4:5], v[26:27]
	v_pk_mul_f32 v[32:33], v[10:11], v[32:33]
	v_pk_mul_f32 v[30:31], v[8:9], v[30:31]
	v_pk_mul_f32 v[36:37], v[14:15], v[36:37]
	v_pk_mul_f32 v[34:35], v[12:13], v[34:35]
	global_store_dwordx4 v[38:39], v[22:25], off
	global_store_dwordx4 v[38:39], v[26:29], off offset:1024
	global_store_dwordx4 v[38:39], v[30:33], off offset:2048
	global_store_dwordx4 v[38:39], v[34:37], off offset:3072
	s_cbranch_scc1 .LBB0_1049
